# re-balance after the faster sample units: pooling/kv items 0..1343 on workgroups 64..255
# speedup vs baseline: 1.0051x; 1.0051x over previous
; __device__ __forceinline__ void run_phase(const Params& p, int ph, LAS unsigned char* lds, const int tid, const int bid) {
;     ...
;     } else if (sub == 1) { if (PH_MASK & 4)
;         for (int it = bid; it < 1024 + 544 + 580; it += G) {
;             if (it < 1024) sample_ret_unit(p, l, it, lds, tid);
;             else if (it < 1568) kv_unit(p, it - 1024, lds, tid);
;             else pool_item(p, l, it - 1568, tid);
;         }
.LBB0_447:
	s_andn2_b64 vcc, exec, s[0:1]
	s_cbranch_vccnz .LBB0_582
	v_readlane_b32 s0, v254, 48
	s_and_b32 s0, 0xffff, s0
	s_cmp_gt_i32 s0, 0
	s_mov_b64 s[0:1], -1
	s_cbranch_scc0 .LBB0_547
	s_cmpk_gt_i32 s82, 0x863
	s_cbranch_scc1 .LBB0_546
	v_readlane_b32 s0, v254, 46
	v_readlane_b32 s1, v254, 47
	s_mov_b32 s1, s91
	v_readlane_b32 s8, v253, 57
	s_lshl_b64 s[22:23], s[0:1], 7
	s_lshl_b64 s[24:25], s[0:1], 2
	s_lshl_b64 s[26:27], s[0:1], 10
	s_mov_b32 s6, s0
	s_lshl_b64 s[0:1], s[0:1], 13
	v_readlane_b32 s10, v253, 59
	v_readlane_b32 s11, v253, 60
	s_add_u32 s34, s10, s0
	v_writelane_b32 v254, s6, 46
	s_addc_u32 s35, s11, s1
	s_mov_b32 s38, s82
	s_cmpk_lg_u32 s42, 0x100
	s_cbranch_scc1 .Lp2_fwd0
	s_bitcmp1_b32 s82, 3
	s_cbranch_scc1 .Lz2_ibwd
	s_mov_b32 s0, 0
	s_add_i32 s38, s82, 0xffffffc0
	s_cmpk_gt_u32 s82, 63
	s_cbranch_scc1 .Lz2_iset
	s_mov_b32 s0, 1
	s_add_i32 s38, s82, 0x540
	s_branch .Lz2_iset
.Lz2_ibwd:
	s_mov_b32 s0, 1
	s_sub_i32 s38, 0x323, s82
	s_andn2_b32 s38, s38, 0xff
	s_add_i32 s38, s38, s82
	s_add_i32 s38, s38, 0x540

; __device__ __forceinline__ void run_phase(const Params& p, int ph, LAS unsigned char* lds, const int tid, const int bid) {
;     ...
;     } else if (sub == 1) { if (PH_MASK & 4)
;         for (int it = bid; it < 1024 + 544 + 580; it += G) {
;             if (it < 1024) sample_ret_unit(p, l, it, lds, tid);
;             else if (it < 1568) kv_unit(p, it - 1024, lds, tid);
;             else pool_item(p, l, it - 1568, tid);
;         }
.LBB0_451:
	s_cmpk_lg_u32 s42, 0x100
	s_cbranch_scc1 .Lz2_generic
	v_readlane_b32 s1, v255, 9
	s_bitcmp1_b32 s82, 3
	s_cbranch_scc1 .Lz2_lbwd
	s_cmp_eq_u32 s1, 0
	s_cbranch_scc0 .Lz2_fB
	s_addk_i32 s38, 0xc0
	s_cmpk_lt_i32 s38, 0x540
	s_cbranch_scc1 .Lz2_lset
	s_mov_b32 s1, 1
	s_nop 0
	v_writelane_b32 v255, s1, 9
	s_add_i32 s38, s82, 0x540
	s_branch .Lz2_lset

; __device__ __forceinline__ void run_phase(const Params& p, int ph, LAS unsigned char* lds, const int tid, const int bid) {
;     ...
;     } else if (sub == 1) { if (PH_MASK & 4)
;         for (int it = bid; it < 1024 + 544 + 580; it += G) {
;             if (it < 1024) sample_ret_unit(p, l, it, lds, tid);
;             else if (it < 1568) kv_unit(p, it - 1024, lds, tid);
;             else pool_item(p, l, it - 1568, tid);
;         }
.Lz2_lbwd:
	s_cmp_eq_u32 s1, 0
	s_cbranch_scc1 .Lz2_bA
	s_addk_i32 s38, 0xff00
	s_cmpk_ge_i32 s38, 0x540
	s_cbranch_scc1 .Lz2_lset
	s_cmpk_lt_u32 s82, 64
	s_cbranch_scc1 .LBB0_546
	s_mov_b32 s1, 0
	s_nop 0
	v_writelane_b32 v255, s1, 9
	s_add_i32 s38, s82, 0x440
	s_branch .Lz2_lset
